# v75 + P0 w_in weight copy with 8 global_load_dwordx4 per item instead of 32 global_load_dword (same LDS image)
# baseline (speedup 1.0000x reference)
.LBB0_91:
	v_readlane_b32 s16, v254, 0
	v_readlane_b32 s28, v254, 12
	v_readlane_b32 s29, v254, 13
	v_readlane_b32 s17, v254, 1
	v_readlane_b32 s18, v254, 2
	v_readlane_b32 s19, v254, 3
	v_readlane_b32 s20, v254, 4
	v_readlane_b32 s21, v254, 5
	v_readlane_b32 s22, v254, 6
	v_readlane_b32 s23, v254, 7
	v_readlane_b32 s24, v254, 8
	v_readlane_b32 s25, v254, 9
	v_readlane_b32 s26, v254, 10
	v_readlane_b32 s27, v254, 11
	v_readlane_b32 s30, v254, 14
	v_readlane_b32 s31, v254, 15
	v_lshl_or_b32 v12, v0, 5, v31
	v_lshrrev_b32_e32 v13, 3, v12
	v_and_b32_e32 v14, 7, v12
	v_add_u32_e32 v15, s12, v13
	v_mul_u32_u24_e32 v15, 0x2c20, v15
	v_lshl_add_u32 v15, v14, 2, v15
	v_add_u32_e32 v15, s9, v15
	v_lshlrev_b32_e32 v15, 2, v15
	v_mul_u32_u24_e32 v18, 0x84, v13
	v_lshl_add_u32 v18, v14, 4, v18
	v_mul_u32_u24_e32 v58, 0x84, v0
	v_lshl_add_u32 v58, v31, 2, v58
	v_sub_u32_e32 v58, v32, v58
	v_add_u32_e32 v18, v58, v18
	global_load_dwordx4 v[88:91], v15, s[28:29]
	v_add_u32_e32 v16, 0x58400, v15
	global_load_dwordx4 v[92:95], v16, s[28:29]
	v_add_u32_e32 v17, 0xb0800, v15
	global_load_dwordx4 v[96:99], v17, s[28:29]
	v_add_u32_e32 v19, 0x108c00, v15
	global_load_dwordx4 v[100:103], v19, s[28:29]
	v_add_u32_e32 v20, 0x161000, v15
	global_load_dwordx4 v[104:107], v20, s[28:29]
	v_add_u32_e32 v21, 0x1b9400, v15
	global_load_dwordx4 v[108:111], v21, s[28:29]
	v_add_u32_e32 v56, 0x211800, v15
	global_load_dwordx4 v[112:115], v56, s[28:29]
	v_add_u32_e32 v57, 0x269c00, v15
	global_load_dwordx4 v[116:119], v57, s[28:29]
	s_waitcnt vmcnt(7)
	ds_write_b32 v18, v88 offset:0
	ds_write_b32 v18, v89 offset:4
	ds_write_b32 v18, v90 offset:8
	ds_write_b32 v18, v91 offset:12
	s_waitcnt vmcnt(6)
	ds_write_b32 v18, v92 offset:1056
	ds_write_b32 v18, v93 offset:1060
	ds_write_b32 v18, v94 offset:1064
	ds_write_b32 v18, v95 offset:1068
	s_waitcnt vmcnt(5)
	ds_write_b32 v18, v96 offset:2112
	ds_write_b32 v18, v97 offset:2116
	ds_write_b32 v18, v98 offset:2120
	ds_write_b32 v18, v99 offset:2124
	s_waitcnt vmcnt(4)
	ds_write_b32 v18, v100 offset:3168
	ds_write_b32 v18, v101 offset:3172
	ds_write_b32 v18, v102 offset:3176
	ds_write_b32 v18, v103 offset:3180
	s_waitcnt vmcnt(3)
	ds_write_b32 v18, v104 offset:4224
	ds_write_b32 v18, v105 offset:4228
	ds_write_b32 v18, v106 offset:4232
	ds_write_b32 v18, v107 offset:4236
	s_waitcnt vmcnt(2)
	ds_write_b32 v18, v108 offset:5280
	ds_write_b32 v18, v109 offset:5284
	ds_write_b32 v18, v110 offset:5288
	ds_write_b32 v18, v111 offset:5292
	s_waitcnt vmcnt(1)
	ds_write_b32 v18, v112 offset:6336
	ds_write_b32 v18, v113 offset:6340
	ds_write_b32 v18, v114 offset:6344
	ds_write_b32 v18, v115 offset:6348
	s_waitcnt vmcnt(0)
	ds_write_b32 v18, v116 offset:7392
	ds_write_b32 v18, v117 offset:7396
	ds_write_b32 v18, v118 offset:7400
	ds_write_b32 v18, v119 offset:7404
	s_branch .LBB0_21
